# grid barrier: workgroups poll the monotonic cross-XCD arrival counter directly (skips TOPGEN/XGEN release hops) + single-batch scan
# speedup vs baseline: 1.0090x; 1.0028x over previous
.LBB0_499:
	global_atomic_add v3, v[186:187], v193, off sc0
	v_cvt_f32_u32_e32 v1, v2
	v_sub_u32_e32 v4, 0, v2
	v_rcp_iflag_f32_e32 v1, v1
	s_nop 0
	v_mul_f32_e32 v1, 0x4f7ffffe, v1
	v_cvt_u32_f32_e32 v1, v1
	v_mul_lo_u32 v4, v4, v1
	v_mul_hi_u32 v4, v1, v4
	v_add_u32_e32 v1, v1, v4
	s_waitcnt vmcnt(0)
	v_mul_hi_u32 v1, v3, v1
	v_mul_lo_u32 v4, v1, v2
	v_sub_u32_e32 v4, v3, v4
	v_add_u32_e32 v5, 1, v1
	v_cmp_ge_u32_e32 vcc, v4, v2
	v_add_u32_e32 v3, 1, v3
	s_nop 0
	v_cndmask_b32_e32 v1, v1, v5, vcc
	v_sub_u32_e32 v5, v4, v2
	v_cndmask_b32_e32 v4, v4, v5, vcc
	v_add_u32_e32 v5, 1, v1
	v_cmp_ge_u32_e32 vcc, v4, v2
	s_nop 1
	v_cndmask_b32_e32 v1, v1, v5, vcc
	v_mul_lo_u32 v4, v2, v1
	v_add_u32_e32 v2, v4, v2
	v_cmp_ne_u32_e32 vcc, v3, v2
	s_and_saveexec_b64 s[10:11], vcc
	s_xor_b64 s[22:23], exec, s[10:11]
	s_cbranch_execz .LBB0_513
	s_waitcnt lgkmcnt(0)
	v_add_u32_e32 v255, 1, v1
	v_mul_lo_u32 v255, v255, v0
	s_getpc_b64 s[100:101]
	s_add_u32 s100, s100, g_ctl@rel32@lo+13316
	s_addc_u32 s101, s101, g_ctl@rel32@hi+13324
	global_load_dword v0, v191, s[100:101] sc1
	s_waitcnt vmcnt(0)
	v_cmp_lt_u32_e32 vcc, v0, v255
	s_and_saveexec_b64 s[24:25], vcc
	s_cbranch_execz .LBB0_512
	s_mov_b32 s10, 1
	s_mov_b64 s[26:27], 0
	s_branch .LBB0_503

.LBB0_507:
	global_load_dword v0, v191, s[100:101] sc1
	s_add_i32 s10, s10, 1
	s_mov_b64 s[34:35], -1
	s_waitcnt vmcnt(0)
	v_cmp_ge_u32_e32 vcc, v0, v255
	s_orn2_b64 s[30:31], vcc, exec
	s_branch .LBB0_502

.LBB0_516:
	s_or_b64 exec, exec, s[24:25]
	s_waitcnt vmcnt(0)
	v_readfirstlane_b32 s2, v2
	v_cvt_f32_u32_e32 v2, v0
	v_sub_u32_e32 v3, 0, v0
	v_add_u32_e32 v1, s2, v1
	s_getpc_b64 s[28:29]
	s_add_u32 s28, s28, g_ctl@rel32@lo+13572
	s_addc_u32 s29, s29, g_ctl@rel32@hi+13580
	v_rcp_iflag_f32_e32 v2, v2
	s_mov_b64 s[24:25], -1
	v_mul_f32_e32 v2, 0x4f7ffffe, v2
	v_cvt_u32_f32_e32 v2, v2
	v_mul_lo_u32 v3, v3, v2
	v_mul_hi_u32 v3, v2, v3
	v_add_u32_e32 v2, v2, v3
	v_mul_hi_u32 v2, v1, v2
	v_mul_lo_u32 v3, v2, v0
	v_sub_u32_e32 v3, v1, v3
	v_cmp_ge_u32_e32 vcc, v3, v0
	v_add_u32_e32 v4, 1, v2
	v_add_u32_e32 v1, 1, v1
	v_cndmask_b32_e32 v2, v2, v4, vcc
	v_sub_u32_e32 v4, v3, v0
	v_cndmask_b32_e32 v3, v3, v4, vcc
	v_cmp_ge_u32_e32 vcc, v3, v0
	v_add_u32_e32 v3, 1, v2
	s_nop 0
	v_cndmask_b32_e32 v2, v2, v3, vcc
	v_mul_lo_u32 v3, v0, v2
	v_add_u32_e32 v0, v3, v0
	v_mov_b32_e32 v255, v0
	s_getpc_b64 s[100:101]
	s_add_u32 s100, s100, g_ctl@rel32@lo+13316
	s_addc_u32 s101, s101, g_ctl@rel32@hi+13324
	v_cmp_ne_u32_e32 vcc, v1, v0
	v_mov_b64_e32 v[0:1], s[28:29]
	s_and_saveexec_b64 s[22:23], vcc
	s_cbranch_execz .LBB0_528
	global_load_dword v0, v191, s[100:101] sc1
	s_mov_b64 s[26:27], 0
	s_waitcnt vmcnt(0)
	v_cmp_lt_u32_e32 vcc, v0, v255
	v_mov_b64_e32 v[0:1], s[28:29]
	s_and_saveexec_b64 s[24:25], vcc
	s_cbranch_execz .LBB0_527
	s_mov_b32 s10, 1
	s_mov_b64 s[28:29], 0
	s_branch .LBB0_520

.LBB0_524:
	s_getpc_b64 s[12:13]
	s_add_u32 s12, s12, g_ctl@rel32@lo+13572
	s_addc_u32 s13, s13, g_ctl@rel32@hi+13580
	global_load_dword v0, v191, s[100:101] sc1
	s_add_i32 s10, s10, 1
	s_mov_b64 s[34:35], -1
	s_waitcnt vmcnt(0)
	v_cmp_ge_u32_e32 vcc, v0, v255
	s_orn2_b64 s[30:31], vcc, exec
	s_branch .LBB0_519

.LBB0_839:
	global_atomic_add v3, v[186:187], v193, off sc0
	v_cvt_f32_u32_e32 v1, v2
	v_sub_u32_e32 v4, 0, v2
	v_rcp_iflag_f32_e32 v1, v1
	s_nop 0
	v_mul_f32_e32 v1, 0x4f7ffffe, v1
	v_cvt_u32_f32_e32 v1, v1
	v_mul_lo_u32 v4, v4, v1
	v_mul_hi_u32 v4, v1, v4
	v_add_u32_e32 v1, v1, v4
	s_waitcnt vmcnt(0)
	v_mul_hi_u32 v1, v3, v1
	v_mul_lo_u32 v4, v1, v2
	v_sub_u32_e32 v4, v3, v4
	v_add_u32_e32 v5, 1, v1
	v_cmp_ge_u32_e32 vcc, v4, v2
	v_add_u32_e32 v3, 1, v3
	s_nop 0
	v_cndmask_b32_e32 v1, v1, v5, vcc
	v_sub_u32_e32 v5, v4, v2
	v_cndmask_b32_e32 v4, v4, v5, vcc
	v_add_u32_e32 v5, 1, v1
	v_cmp_ge_u32_e32 vcc, v4, v2
	s_nop 1
	v_cndmask_b32_e32 v1, v1, v5, vcc
	v_mul_lo_u32 v4, v2, v1
	v_add_u32_e32 v2, v4, v2
	v_cmp_ne_u32_e32 vcc, v3, v2
	s_and_saveexec_b64 s[2:3], vcc
	s_xor_b64 s[12:13], exec, s[2:3]
	s_cbranch_execz .LBB0_853
	s_waitcnt lgkmcnt(0)
	v_add_u32_e32 v255, 1, v1
	v_mul_lo_u32 v255, v255, v0
	s_getpc_b64 s[100:101]
	s_add_u32 s100, s100, g_ctl@rel32@lo+13316
	s_addc_u32 s101, s101, g_ctl@rel32@hi+13324
	global_load_dword v0, v191, s[100:101] sc1
	s_waitcnt vmcnt(0)
	v_cmp_lt_u32_e32 vcc, v0, v255
	s_and_saveexec_b64 s[14:15], vcc
	s_cbranch_execz .LBB0_852
	s_mov_b32 s20, 1
	s_mov_b64 s[16:17], 0
	s_branch .LBB0_843

.LBB0_847:
	global_load_dword v0, v191, s[100:101] sc1
	s_add_i32 s20, s20, 1
	s_mov_b64 s[24:25], -1
	s_waitcnt vmcnt(0)
	v_cmp_ge_u32_e32 vcc, v0, v255
	s_orn2_b64 s[22:23], vcc, exec
	s_branch .LBB0_842

.LBB0_856:
	s_or_b64 exec, exec, s[14:15]
	s_waitcnt vmcnt(0)
	v_readfirstlane_b32 s2, v2
	v_cvt_f32_u32_e32 v2, v0
	v_sub_u32_e32 v3, 0, v0
	v_add_u32_e32 v1, s2, v1
	s_getpc_b64 s[18:19]
	s_add_u32 s18, s18, g_ctl@rel32@lo+13572
	s_addc_u32 s19, s19, g_ctl@rel32@hi+13580
	v_rcp_iflag_f32_e32 v2, v2
	s_mov_b64 s[14:15], -1
	v_mul_f32_e32 v2, 0x4f7ffffe, v2
	v_cvt_u32_f32_e32 v2, v2
	v_mul_lo_u32 v3, v3, v2
	v_mul_hi_u32 v3, v2, v3
	v_add_u32_e32 v2, v2, v3
	v_mul_hi_u32 v2, v1, v2
	v_mul_lo_u32 v3, v2, v0
	v_sub_u32_e32 v3, v1, v3
	v_cmp_ge_u32_e32 vcc, v3, v0
	v_add_u32_e32 v4, 1, v2
	v_add_u32_e32 v1, 1, v1
	v_cndmask_b32_e32 v2, v2, v4, vcc
	v_sub_u32_e32 v4, v3, v0
	v_cndmask_b32_e32 v3, v3, v4, vcc
	v_cmp_ge_u32_e32 vcc, v3, v0
	v_add_u32_e32 v3, 1, v2
	s_nop 0
	v_cndmask_b32_e32 v2, v2, v3, vcc
	v_mul_lo_u32 v3, v0, v2
	v_add_u32_e32 v0, v3, v0
	v_mov_b32_e32 v255, v0
	s_getpc_b64 s[100:101]
	s_add_u32 s100, s100, g_ctl@rel32@lo+13316
	s_addc_u32 s101, s101, g_ctl@rel32@hi+13324
	v_cmp_ne_u32_e32 vcc, v1, v0
	v_mov_b64_e32 v[0:1], s[18:19]
	s_and_saveexec_b64 s[12:13], vcc
	s_cbranch_execz .LBB0_868
	global_load_dword v0, v191, s[100:101] sc1
	s_mov_b64 s[16:17], 0
	s_waitcnt vmcnt(0)
	v_cmp_lt_u32_e32 vcc, v0, v255
	v_mov_b64_e32 v[0:1], s[18:19]
	s_and_saveexec_b64 s[14:15], vcc
	s_cbranch_execz .LBB0_867
	s_mov_b32 s20, 1
	s_mov_b64 s[18:19], 0
	s_branch .LBB0_860

.LBB0_864:
	s_getpc_b64 s[2:3]
	s_add_u32 s2, s2, g_ctl@rel32@lo+13572
	s_addc_u32 s3, s3, g_ctl@rel32@hi+13580
	global_load_dword v0, v191, s[100:101] sc1
	s_add_i32 s20, s20, 1
	s_mov_b64 s[24:25], -1
	s_waitcnt vmcnt(0)
	v_cmp_ge_u32_e32 vcc, v0, v255
	s_orn2_b64 s[22:23], vcc, exec
	s_branch .LBB0_859
